# attention unit boundary: head-norm gains loaded in one batch, lambda scalars read once per phase, no store drain at the unit head, unused per-unit bias table dropped
# baseline (speedup 1.0000x reference)
.LBB0_195:
	v_readlane_b32 s68, v240, 16
	v_readlane_b32 s84, v240, 29
	v_readlane_b32 s98, v240, 27
	s_andn2_b64 vcc, exec, s[46:47]
	v_readlane_b32 s69, v240, 17
	v_readlane_b32 s70, v240, 18
	v_readlane_b32 s71, v240, 19
	v_readlane_b32 s72, v240, 20
	v_readlane_b32 s73, v240, 21
	v_readlane_b32 s74, v240, 22
	v_readlane_b32 s75, v240, 23
	v_readlane_b32 s85, v240, 30
	s_mov_b64 s[86:87], s[50:51]
	v_readlane_b32 s99, v240, 28
	v_readlane_b32 s58, v240, 24
	s_cbranch_vccnz .LBB0_226
	s_mov_b32 s20, s81
	v_readlane_b32 s0, v242, 49
	v_readlane_b32 s1, v242, 50
	s_andn2_b64 vcc, exec, s[0:1]
	s_cbranch_vccnz .LBB0_225
	v_readlane_b32 s47, v240, 33
	s_lshl_b32 s0, s47, 4
	v_readlane_b32 s2, v242, 12
	v_readlane_b32 s3, v242, 13
	s_add_u32 s0, s2, s0
	s_addc_u32 s1, s3, 0
	s_lshl_b32 s2, s47, 9
	s_add_u32 s2, s68, s2
	s_addc_u32 s3, s69, 0
	v_readlane_b32 s21, v243, 3
	global_load_dwordx2 v[2:3], v1, s[0:1]
	s_waitcnt vmcnt(0)
	v_readfirstlane_b32 s100, v2
	v_readfirstlane_b32 s101, v3
	s_bfe_u32 s4, s21, 0x30003
	s_lshl_b32 s4, s4, 7
	v_sub_u32_e32 v2, 0xff, v172
	v_min_i32_e32 v3, v2, v184
	v_max_i32_e32 v3, 0, v3
	v_add_u32_e32 v3, s4, v3
	v_lshlrev_b32_e32 v3, 2, v3
	global_load_dword v4, v3, s[76:77]
	v_lshlrev_b32_e32 v5, 2, v172
	v_add_u32_e32 v5, 0x20800, v5
	v_cmp_gt_i32_e32 vcc, 0, v2
	s_waitcnt vmcnt(0)
	v_cndmask_b32_e32 v4, v4, v173, vcc
	v_cmp_gt_u32_e32 vcc, 0x180, v172
	s_and_saveexec_b64 s[6:7], vcc
	ds_write_b32 v5, v4
	s_or_b64 exec, exec, s[6:7]
	s_branch .LBB0_199

.LBB0_199:
	v_mov_b32_e32 v3, v172
	s_and_b32 s5, s21, 7
	v_readfirstlane_b32 s4, v3
	s_ashr_i32 s11, s4, 8
	s_ashr_i32 s8, s4, 6
	s_ashr_i32 s4, s21, 8
	s_sub_i32 s4, 7, s4
	s_and_b32 s6, s4, 1
	s_lshl_b32 s4, s4, 3
	s_or_b32 s7, s4, 15
	s_sub_i32 s7, s7, s5
	s_or_b32 s4, s4, s5
	s_cmp_eq_u32 s6, 0
	s_cselect_b32 s23, s4, s7
	s_bfe_u32 s16, s21, 0x20006
	s_lshl_b32 s5, s8, 5
	v_and_b32_e32 v2, 31, v3
	s_lshl_b32 s9, s23, 7
	s_lshl_b32 s4, s16, 13
	s_and_b32 s10, s5, 0x60
	s_add_i32 s22, s9, s4
	v_or_b32_e32 v0, s10, v2
	v_or_b32_e32 v0, s22, v0
	s_bfe_u32 s17, s21, 0x30003
	v_lshlrev_b64 v[6:7], 11, v[0:1]
	v_lshl_add_u64 v[6:7], s[92:93], 0, v[6:7]
	s_lshl_b32 s80, s17, 8
	s_lshl_b32 s6, s11, 6
	v_bfe_u32 v4, v3, 5, 1
	v_lshl_add_u64 v[6:7], v[6:7], 0, s[80:81]
	s_ashr_i32 s7, s6, 31
	v_lshl_add_u64 v[6:7], s[6:7], 1, v[6:7]
	v_lshlrev_b32_e32 v0, 4, v4
	v_lshl_add_u64 v[6:7], v[6:7], 0, v[0:1]
	global_load_dwordx4 v[128:131], v[6:7], off
	global_load_dwordx4 v[132:135], v[6:7], off offset:32
	global_load_dwordx4 v[136:139], v[6:7], off offset:64
	global_load_dwordx4 v[140:143], v[6:7], off offset:96
	s_lshl_b32 s18, s17, 7
	s_lshr_b32 s5, s21, 6
	s_lshr_b32 s6, s21, 3
	s_and_b32 s5, s5, 3
	s_and_b32 s6, s6, 7
	v_and_b32_e32 v0, 63, v3
	s_lshl_b32 s6, s6, 21
	s_lshl_b32 s5, s5, 24
	s_or_b32 s19, s5, s6
	s_lshl_b32 s5, s8, 2
	v_lshrrev_b32_e32 v5, 4, v0
	v_or_b32_e32 v6, s5, v5
	v_bitop3_b32 v5, s5, v3, v5 bitop3:0x36
	s_mov_b32 s5, s81
	v_ashrrev_i32_e32 v7, 31, v6
	v_lshl_add_u64 v[6:7], v[6:7], 0, s[4:5]
	v_lshlrev_b64 v[6:7], 11, v[6:7]
	v_lshl_add_u64 v[6:7], s[86:87], 0, v[6:7]
	s_lshl_b32 s4, s18, 1
	v_lshrrev_b32_e32 v10, 3, v0
	v_lshl_add_u64 v[6:7], v[6:7], 0, s[4:5]
	s_lshl_b32 s5, s17, 21
	s_lshl_b32 s6, s16, 24
	v_lshl_or_b32 v0, s8, 3, v10
	s_lshl_b32 s24, s8, 10
	s_or_b32 s5, s6, s5
	v_lshrrev_b32_e32 v11, 1, v0
	v_lshlrev_b32_e32 v8, 6, v0
	v_lshlrev_b32_e32 v0, 4, v5
	s_add_u32 s6, s98, s5
	v_xor_b32_e32 v12, v11, v3
	v_and_b32_e32 v0, 0xf0, v0
	s_addc_u32 s7, s99, 0
	s_add_i32 s5, s24, 0
	v_ashrrev_i32_e32 v9, 31, v8
	v_lshl_add_u64 v[144:145], v[6:7], 0, v[0:1]
	v_lshlrev_b32_e32 v0, 4, v12
	s_mov_b32 m0, s5
	v_lshl_add_u64 v[6:7], v[8:9], 1, s[6:7]
	v_and_b32_e32 v0, 0x70, v0
	global_load_lds_dwordx4 v[144:145], off
	v_lshl_add_u64 v[8:9], v[144:145], 0, s[60:61]
	s_add_i32 m0, s5, 0x2000
	v_lshl_add_u64 v[6:7], v[6:7], 0, v[0:1]
	global_load_lds_dwordx4 v[8:9], off
	s_add_i32 m0, s5, 0x10000
	v_lshl_add_u64 v[8:9], v[6:7], 0, s[44:45]
	global_load_lds_dwordx4 v[6:7], off
	s_add_i32 m0, s5, 0x12000
	s_mov_b64 s[6:7], 0x20000
	global_load_lds_dwordx4 v[8:9], off
	v_lshl_add_u64 v[8:9], v[144:145], 0, s[6:7]
	s_add_i32 m0, s5, 0x4000
	s_mov_b64 s[6:7], 0x30000
	global_load_lds_dwordx4 v[8:9], off
	v_lshl_add_u64 v[8:9], v[144:145], 0, s[6:7]
	s_add_i32 m0, s5, 0x6000
	s_mov_b64 s[6:7], 0x4000
	global_load_lds_dwordx4 v[8:9], off
	v_lshl_add_u64 v[8:9], v[6:7], 0, s[6:7]
	s_add_i32 m0, s5, 0x14000
	s_mov_b64 s[6:7], 0x6000
	global_load_lds_dwordx4 v[8:9], off
	v_lshl_add_u64 v[6:7], v[6:7], 0, s[6:7]
	s_add_i32 m0, s5, 0x16000
	v_and_b32_e32 v5, 19, v3
	global_load_lds_dwordx4 v[6:7], off
	v_lshlrev_b32_e32 v6, 1, v3
	v_lshrrev_b32_e32 v7, 1, v3
	v_and_b32_e32 v6, 8, v6
	v_and_b32_e32 v8, 4, v7
	v_lshlrev_b32_e32 v0, 3, v4
	v_or3_b32 v5, v6, v5, v8
	v_lshl_or_b32 v6, s11, 3, v4
	v_bitop3_b32 v4, v4, v7, 7 bitop3:0x78
	v_lshlrev_b32_e32 v149, 4, v4
	v_lshlrev_b32_e32 v4, 6, v10
	v_lshl_or_b32 v4, s8, 9, v4
	v_bitop3_b32 v6, v5, v6, 15 bitop3:0x6c
	v_lshlrev_b32_e32 v156, 8, v5
	s_add_i32 s5, s23, -1
	s_add_i32 s25, s23, 1
	v_ashrrev_i32_e32 v5, 31, v4
	v_bitop3_b32 v3, v11, 7, v3 bitop3:0x48
	v_lshlrev_b64 v[4:5], 1, v[4:5]
	s_add_u32 s6, s76, s19
	v_lshl_or_b32 v4, v3, 4, v4
	s_addc_u32 s7, s77, 0
	v_lshl_add_u64 v[146:147], s[6:7], 0, v[4:5]
	s_add_i32 s6, s9, s10
	s_addk_i32 s6, 0xff89
	v_lshlrev_b32_e32 v157, 7, v2
	v_add_u32_e32 v2, s6, v2
	v_mov_b32_e32 v14, v1
	v_mov_b32_e32 v15, v1
	v_lshlrev_b32_e32 v148, 4, v6
	v_sub_u32_e32 v158, v2, v0
	v_mov_b32_e32 v0, v1
	v_mov_b32_e32 v2, v1
	v_mov_b32_e32 v3, v1
	v_mov_b32_e32 v4, v1
	v_mov_b32_e32 v5, v1
	v_mov_b32_e32 v6, v1
	v_mov_b32_e32 v7, v1
	v_mov_b32_e32 v8, v1
	v_mov_b32_e32 v9, v1
	v_mov_b32_e32 v10, v1
	v_mov_b32_e32 v11, v1
	v_mov_b32_e32 v12, v1
	v_mov_b32_e32 v13, v1
	v_mov_b64_e32 v[30:31], v[14:15]
	v_mov_b64_e32 v[46:47], v[14:15]
	v_mov_b64_e32 v[62:63], v[14:15]
	v_mov_b64_e32 v[78:79], v[14:15]
	v_mov_b64_e32 v[94:95], v[14:15]
	v_xor_b32_e32 v150, 32, v148
	v_xor_b32_e32 v151, 32, v149
	v_xor_b32_e32 v152, 64, v148
	v_xor_b32_e32 v153, 64, v149
	v_xor_b32_e32 v154, 0x60, v148
	v_xor_b32_e32 v155, 0x60, v149
	s_mov_b32 s26, 0
	v_mov_b32_e32 v159, 0
	s_mov_b64 s[6:7], 0
	s_movk_i32 s8, 0xc0
	v_mov_b64_e32 v[28:29], v[12:13]
	v_mov_b64_e32 v[26:27], v[10:11]
	v_mov_b64_e32 v[24:25], v[8:9]
	v_mov_b64_e32 v[22:23], v[6:7]
	v_mov_b64_e32 v[20:21], v[4:5]
	v_mov_b64_e32 v[18:19], v[2:3]
	v_mov_b64_e32 v[16:17], v[0:1]
	v_mov_b64_e32 v[44:45], v[12:13]
	v_mov_b64_e32 v[42:43], v[10:11]
	v_mov_b64_e32 v[40:41], v[8:9]
	v_mov_b64_e32 v[38:39], v[6:7]
	v_mov_b64_e32 v[36:37], v[4:5]
	v_mov_b64_e32 v[34:35], v[2:3]
	v_mov_b64_e32 v[32:33], v[0:1]
	v_mov_b64_e32 v[60:61], v[12:13]
	v_mov_b64_e32 v[58:59], v[10:11]
	v_mov_b64_e32 v[56:57], v[8:9]
	v_mov_b64_e32 v[54:55], v[6:7]
	v_mov_b64_e32 v[52:53], v[4:5]
	v_mov_b64_e32 v[50:51], v[2:3]
	v_mov_b64_e32 v[48:49], v[0:1]
	v_mov_b64_e32 v[76:77], v[12:13]
	v_mov_b64_e32 v[74:75], v[10:11]
	v_mov_b64_e32 v[72:73], v[8:9]
	v_mov_b64_e32 v[70:71], v[6:7]
	v_mov_b64_e32 v[68:69], v[4:5]
	v_mov_b64_e32 v[66:67], v[2:3]
	v_mov_b64_e32 v[64:65], v[0:1]
	v_mov_b64_e32 v[92:93], v[12:13]
	v_mov_b64_e32 v[90:91], v[10:11]
	v_mov_b64_e32 v[88:89], v[8:9]
	v_mov_b64_e32 v[86:87], v[6:7]
	v_mov_b64_e32 v[84:85], v[4:5]
	v_mov_b64_e32 v[82:83], v[2:3]
	v_mov_b64_e32 v[80:81], v[0:1]
	s_waitcnt vmcnt(0)
	s_branch .LBB0_205

.LBB0_221:
	v_mov_b32_e32 v0, v172
	s_waitcnt vmcnt(0)
	s_barrier
	v_mov_b32_e32 v2, s100
	v_mov_b32_e32 v3, s101
	v_and_b32_e32 v6, 64, v185
	v_xor_b32_e32 v5, 32, v185
	v_add_u32_e32 v6, 64, v6
	v_cmp_lt_i32_e32 vcc, v5, v6
	v_and_b32_e32 v4, 31, v0
	v_bfe_u32 v80, v0, 5, 1
	v_cndmask_b32_e32 v5, v185, v5, vcc
	v_lshlrev_b32_e32 v5, 2, v5
	ds_bpermute_b32 v6, v5, v159
	v_readfirstlane_b32 s5, v0
	s_ashr_i32 s6, s5, 6
	s_and_b32 s5, s6, 3
	s_cmp_lt_i32 s6, 4
	s_waitcnt lgkmcnt(0)
	v_add_f32_e32 v0, v159, v6
	v_rcp_f32_e32 v0, v0
	v_lshlrev_b32_e32 v6, 2, v4
	v_lshl_add_u32 v7, v80, 9, 0
	s_cbranch_scc1 .LBB0_223
	s_waitcnt vmcnt(0)
	v_mul_f32_e32 v2, v2, v0
	s_lshl_b32 s7, s5, 14
	v_mul_f32_e32 v8, v64, v2
	v_add3_u32 v9, v7, v6, s7
	v_mul_f32_e32 v10, v65, v2
	ds_write2_b32 v9, v8, v10 offset1:32
	v_mul_f32_e32 v8, v66, v2
	v_mul_f32_e32 v10, v67, v2
	ds_write2_b32 v9, v8, v10 offset0:64 offset1:96
	v_mul_f32_e32 v8, v68, v2
	v_mul_f32_e32 v10, v69, v2
	v_add_u32_e32 v11, 0x400, v9
	ds_write2_b32 v11, v8, v10 offset1:32
	v_mul_f32_e32 v8, v70, v2
	v_mul_f32_e32 v10, v71, v2
	ds_write2_b32 v11, v8, v10 offset0:64 offset1:96
	v_mul_f32_e32 v8, v72, v2
	v_mul_f32_e32 v10, v73, v2
	v_add_u32_e32 v11, 0x800, v9
	ds_write2_b32 v11, v8, v10 offset1:32
	v_mul_f32_e32 v8, v74, v2
	v_mul_f32_e32 v10, v75, v2
	ds_write2_b32 v11, v8, v10 offset0:64 offset1:96
	v_mul_f32_e32 v8, v76, v2
	v_mul_f32_e32 v10, v77, v2
	v_add_u32_e32 v11, 0xc00, v9
	ds_write2_b32 v11, v8, v10 offset1:32
	v_mul_f32_e32 v8, v78, v2
	v_mul_f32_e32 v10, v79, v2
	ds_write2_b32 v11, v8, v10 offset0:64 offset1:96
	v_mul_f32_e32 v8, v48, v2
	v_mul_f32_e32 v10, v49, v2
	v_add_u32_e32 v11, 0x1000, v9
	ds_write2_b32 v11, v8, v10 offset1:32
	v_mul_f32_e32 v8, v50, v2
	v_mul_f32_e32 v10, v51, v2
	ds_write2_b32 v11, v8, v10 offset0:64 offset1:96
	v_mul_f32_e32 v8, v52, v2
	v_mul_f32_e32 v10, v53, v2
	v_add_u32_e32 v11, 0x1400, v9
	ds_write2_b32 v11, v8, v10 offset1:32
	v_mul_f32_e32 v8, v54, v2
	v_mul_f32_e32 v10, v55, v2
	ds_write2_b32 v11, v8, v10 offset0:64 offset1:96
	v_mul_f32_e32 v8, v56, v2
	v_mul_f32_e32 v10, v57, v2
	v_add_u32_e32 v11, 0x1800, v9
	ds_write2_b32 v11, v8, v10 offset1:32
	v_mul_f32_e32 v8, v58, v2
	v_mul_f32_e32 v10, v59, v2
	ds_write2_b32 v11, v8, v10 offset0:64 offset1:96
	v_mul_f32_e32 v8, v60, v2
	v_mul_f32_e32 v10, v61, v2
	v_add_u32_e32 v11, 0x1c00, v9
	ds_write2_b32 v11, v8, v10 offset1:32
	v_mul_f32_e32 v8, v62, v2
	v_mul_f32_e32 v10, v63, v2
	ds_write2_b32 v11, v8, v10 offset0:64 offset1:96
	v_mul_f32_e32 v8, v32, v2
	v_mul_f32_e32 v10, v33, v2
	v_add_u32_e32 v11, 0x2000, v9
	ds_write2_b32 v11, v8, v10 offset1:32
	v_mul_f32_e32 v8, v34, v2
	v_mul_f32_e32 v10, v35, v2
	ds_write2_b32 v11, v8, v10 offset0:64 offset1:96
	v_mul_f32_e32 v8, v36, v2
	v_mul_f32_e32 v10, v37, v2
	v_add_u32_e32 v11, 0x2400, v9
	ds_write2_b32 v11, v8, v10 offset1:32
	v_mul_f32_e32 v8, v38, v2
	v_mul_f32_e32 v10, v39, v2
	ds_write2_b32 v11, v8, v10 offset0:64 offset1:96
	v_mul_f32_e32 v8, v40, v2
	v_mul_f32_e32 v10, v41, v2
	v_add_u32_e32 v11, 0x2800, v9
	ds_write2_b32 v11, v8, v10 offset1:32
	v_mul_f32_e32 v8, v42, v2
	v_mul_f32_e32 v10, v43, v2
	ds_write2_b32 v11, v8, v10 offset0:64 offset1:96
	v_mul_f32_e32 v8, v44, v2
	v_mul_f32_e32 v10, v45, v2
	v_add_u32_e32 v11, 0x2c00, v9
	ds_write2_b32 v11, v8, v10 offset1:32
	v_mul_f32_e32 v8, v46, v2
	v_mul_f32_e32 v10, v47, v2
	ds_write2_b32 v11, v8, v10 offset0:64 offset1:96
	v_mul_f32_e32 v8, v16, v2
	v_mul_f32_e32 v10, v17, v2
	v_add_u32_e32 v11, 0x3000, v9
	ds_write2_b32 v11, v8, v10 offset1:32
	v_mul_f32_e32 v8, v18, v2
	v_mul_f32_e32 v10, v19, v2
	ds_write2_b32 v11, v8, v10 offset0:64 offset1:96
	v_mul_f32_e32 v8, v20, v2
	v_mul_f32_e32 v10, v21, v2
	v_add_u32_e32 v11, 0x3400, v9
	ds_write2_b32 v11, v8, v10 offset1:32
	v_mul_f32_e32 v8, v22, v2
	v_mul_f32_e32 v10, v23, v2
	ds_write2_b32 v11, v8, v10 offset0:64 offset1:96
	v_mul_f32_e32 v8, v24, v2
	v_mul_f32_e32 v10, v25, v2
	v_add_u32_e32 v11, 0x3800, v9
	ds_write2_b32 v11, v8, v10 offset1:32
	v_mul_f32_e32 v8, v26, v2
	v_mul_f32_e32 v10, v27, v2
	ds_write2_b32 v11, v8, v10 offset0:64 offset1:96
	v_mul_f32_e32 v8, v28, v2
	v_mul_f32_e32 v10, v29, v2
	v_add_u32_e32 v9, 0x3c00, v9
	ds_write2_b32 v9, v8, v10 offset1:32
	v_mul_f32_e32 v8, v30, v2
	v_mul_f32_e32 v2, v31, v2
	ds_write2_b32 v9, v8, v2 offset0:64 offset1:96
.LBB0_223:
	s_cmp_gt_i32 s6, 3
	s_waitcnt lgkmcnt(0)
	s_barrier
	s_cbranch_scc1 .LBB0_198
	s_lshl_b32 s6, s5, 14
	s_waitcnt vmcnt(0)
	v_add3_u32 v2, v7, v6, s6
	ds_read2_b32 v[6:7], v2 offset1:32
	ds_read2_b32 v[8:9], v2 offset0:64 offset1:96
	s_waitcnt lgkmcnt(1)
	v_fma_f32 v81, v64, v0, -v6
	v_fma_f32 v64, v65, v0, -v7
	v_add_u32_e32 v7, 0x400, v2
	s_waitcnt lgkmcnt(0)
	v_fma_f32 v65, v66, v0, -v8
	v_fma_f32 v66, v67, v0, -v9
	ds_read2_b32 v[8:9], v7 offset1:32
	v_mul_f32_e32 v6, v64, v64
	v_fmac_f32_e32 v6, v81, v81
	v_fmac_f32_e32 v6, v65, v65
	v_fmac_f32_e32 v6, v66, v66
	s_waitcnt lgkmcnt(0)
	v_fma_f32 v67, v68, v0, -v8
	v_fma_f32 v68, v69, v0, -v9
	ds_read2_b32 v[8:9], v7 offset0:64 offset1:96
	v_add_u32_e32 v7, 0x800, v2
	v_fmac_f32_e32 v6, v67, v67
	v_fmac_f32_e32 v6, v68, v68
	s_waitcnt lgkmcnt(0)
	v_fma_f32 v69, v70, v0, -v8
	v_fma_f32 v70, v71, v0, -v9
	ds_read2_b32 v[8:9], v7 offset1:32
	v_fmac_f32_e32 v6, v69, v69
	v_fmac_f32_e32 v6, v70, v70
	s_waitcnt lgkmcnt(0)
	v_fma_f32 v72, v72, v0, -v8
	v_fma_f32 v71, v73, v0, -v9
	ds_read2_b32 v[8:9], v7 offset0:64 offset1:96
	v_add_u32_e32 v7, 0xc00, v2
	v_fmac_f32_e32 v6, v72, v72
	v_fmac_f32_e32 v6, v71, v71
	s_waitcnt lgkmcnt(0)
	v_fma_f32 v82, v74, v0, -v8
	v_fma_f32 v75, v75, v0, -v9
	ds_read2_b32 v[8:9], v7 offset1:32
	v_fmac_f32_e32 v6, v82, v82
	v_fmac_f32_e32 v6, v75, v75
	s_waitcnt lgkmcnt(0)
	v_fma_f32 v74, v76, v0, -v8
	v_fma_f32 v73, v77, v0, -v9
	ds_read2_b32 v[8:9], v7 offset0:64 offset1:96
	v_add_u32_e32 v7, 0x1000, v2
	v_fmac_f32_e32 v6, v74, v74
	v_fmac_f32_e32 v6, v73, v73
	s_waitcnt lgkmcnt(0)
	v_fma_f32 v78, v78, v0, -v8
	v_fma_f32 v77, v79, v0, -v9
	ds_read2_b32 v[8:9], v7 offset1:32
	v_fmac_f32_e32 v6, v78, v78
	v_fmac_f32_e32 v6, v77, v77
	s_waitcnt lgkmcnt(0)
	v_fma_f32 v76, v48, v0, -v8
	v_fma_f32 v48, v49, v0, -v9
	ds_read2_b32 v[8:9], v7 offset0:64 offset1:96
	v_add_u32_e32 v7, 0x1400, v2
	v_fmac_f32_e32 v6, v76, v76
	v_fmac_f32_e32 v6, v48, v48
	s_waitcnt lgkmcnt(0)
	v_fma_f32 v79, v50, v0, -v8
	v_fma_f32 v51, v51, v0, -v9
	ds_read2_b32 v[8:9], v7 offset1:32
	v_fmac_f32_e32 v6, v79, v79
	v_fmac_f32_e32 v6, v51, v51
	s_waitcnt lgkmcnt(0)
	v_fma_f32 v50, v52, v0, -v8
	v_fma_f32 v49, v53, v0, -v9
	ds_read2_b32 v[8:9], v7 offset0:64 offset1:96
	v_add_u32_e32 v7, 0x1800, v2
	v_fmac_f32_e32 v6, v50, v50
	v_fmac_f32_e32 v6, v49, v49
	s_waitcnt lgkmcnt(0)
	v_fma_f32 v83, v54, v0, -v8
	v_fma_f32 v54, v55, v0, -v9
	ds_read2_b32 v[8:9], v7 offset1:32
	v_fmac_f32_e32 v6, v83, v83
	v_fmac_f32_e32 v6, v54, v54
	s_waitcnt lgkmcnt(0)
	v_fma_f32 v53, v56, v0, -v8
	v_fma_f32 v52, v57, v0, -v9
	ds_read2_b32 v[8:9], v7 offset0:64 offset1:96
	v_add_u32_e32 v7, 0x1c00, v2
	v_fmac_f32_e32 v6, v53, v53
	v_fmac_f32_e32 v6, v52, v52
	s_waitcnt lgkmcnt(0)
	v_fma_f32 v58, v58, v0, -v8
	v_fma_f32 v57, v59, v0, -v9
	ds_read2_b32 v[8:9], v7 offset1:32
	v_fmac_f32_e32 v6, v58, v58
	v_fmac_f32_e32 v6, v57, v57
	s_waitcnt lgkmcnt(0)
	v_fma_f32 v56, v60, v0, -v8
	v_fma_f32 v55, v61, v0, -v9
	ds_read2_b32 v[8:9], v7 offset0:64 offset1:96
	v_add_u32_e32 v7, 0x2000, v2
	v_fmac_f32_e32 v6, v56, v56
	v_fmac_f32_e32 v6, v55, v55
	s_waitcnt lgkmcnt(0)
	v_fma_f32 v61, v62, v0, -v8
	v_fma_f32 v60, v63, v0, -v9
	ds_read2_b32 v[8:9], v7 offset1:32
	v_fmac_f32_e32 v6, v61, v61
	v_fmac_f32_e32 v6, v60, v60
	s_waitcnt lgkmcnt(0)
	v_fma_f32 v59, v32, v0, -v8
	v_fma_f32 v32, v33, v0, -v9
	ds_read2_b32 v[8:9], v7 offset0:64 offset1:96
	v_add_u32_e32 v7, 0x2400, v2
	v_fmac_f32_e32 v6, v59, v59
	v_fmac_f32_e32 v6, v32, v32
	s_waitcnt lgkmcnt(0)
	v_fma_f32 v63, v34, v0, -v8
	v_fma_f32 v62, v35, v0, -v9
	ds_read2_b32 v[8:9], v7 offset1:32
	v_fmac_f32_e32 v6, v63, v63
	v_fmac_f32_e32 v6, v62, v62
	s_waitcnt lgkmcnt(0)
	v_fma_f32 v36, v36, v0, -v8
	v_fma_f32 v34, v37, v0, -v9
	ds_read2_b32 v[8:9], v7 offset0:64 offset1:96
	v_add_u32_e32 v7, 0x2800, v2
	v_fmac_f32_e32 v6, v36, v36
	v_fmac_f32_e32 v6, v34, v34
	s_waitcnt lgkmcnt(0)
	v_fma_f32 v85, v38, v0, -v8
	v_fma_f32 v84, v39, v0, -v9
	ds_read2_b32 v[8:9], v7 offset1:32
	v_fmac_f32_e32 v6, v85, v85
	v_fmac_f32_e32 v6, v84, v84
	s_waitcnt lgkmcnt(0)
	v_fma_f32 v40, v40, v0, -v8
	v_fma_f32 v39, v41, v0, -v9
	ds_read2_b32 v[8:9], v7 offset0:64 offset1:96
	v_add_u32_e32 v7, 0x2c00, v2
	v_fmac_f32_e32 v6, v40, v40
	v_fmac_f32_e32 v6, v39, v39
	s_waitcnt lgkmcnt(0)
	v_fma_f32 v87, v42, v0, -v8
	v_fma_f32 v86, v43, v0, -v9
	ds_read2_b32 v[8:9], v7 offset1:32
	v_fmac_f32_e32 v6, v87, v87
	v_fmac_f32_e32 v6, v86, v86
	s_waitcnt lgkmcnt(0)
	v_fma_f32 v44, v44, v0, -v8
	v_fma_f32 v43, v45, v0, -v9
	ds_read2_b32 v[8:9], v7 offset0:64 offset1:96
	v_add_u32_e32 v7, 0x3000, v2
	v_fmac_f32_e32 v6, v44, v44
	v_fmac_f32_e32 v6, v43, v43
	s_waitcnt lgkmcnt(0)
	v_fma_f32 v42, v46, v0, -v8
	v_fma_f32 v41, v47, v0, -v9
	ds_read2_b32 v[8:9], v7 offset1:32
	v_fmac_f32_e32 v6, v42, v42
	v_fmac_f32_e32 v6, v41, v41
	s_waitcnt lgkmcnt(0)
	v_fma_f32 v38, v16, v0, -v8
	v_fma_f32 v37, v17, v0, -v9
	ds_read2_b32 v[8:9], v7 offset0:64 offset1:96
	v_add_u32_e32 v7, 0x3400, v2
	v_fmac_f32_e32 v6, v38, v38
	v_fmac_f32_e32 v6, v37, v37
	s_waitcnt lgkmcnt(0)
	v_fma_f32 v35, v18, v0, -v8
	v_fma_f32 v33, v19, v0, -v9
	ds_read2_b32 v[8:9], v7 offset1:32
	v_fmac_f32_e32 v6, v35, v35
	v_fmac_f32_e32 v6, v33, v33
	s_waitcnt lgkmcnt(0)
	v_fma_f32 v20, v20, v0, -v8
	v_fma_f32 v19, v21, v0, -v9
	ds_read2_b32 v[8:9], v7 offset0:64 offset1:96
	v_fmac_f32_e32 v6, v20, v20
	v_fmac_f32_e32 v6, v19, v19
	v_lshlrev_b32_e32 v21, 4, v80
	s_waitcnt lgkmcnt(0)
	v_pk_fma_f32 v[14:15], v[22:23], v[0:1], v[8:9] op_sel_hi:[1,0,1] neg_lo:[0,0,1] neg_hi:[0,0,1]
	s_nop 0
	v_pk_mul_f32 v[8:9], v[14:15], v[14:15]
	s_nop 0
	v_add_f32_e32 v6, v6, v8
	v_add_f32_e32 v8, v6, v9
	v_add_u32_e32 v9, 0x3800, v2
	ds_read2_b32 v[6:7], v9 offset1:32
	v_add_u32_e32 v2, 0x3c00, v2
	s_waitcnt lgkmcnt(0)
	v_pk_fma_f32 v[12:13], v[24:25], v[0:1], v[6:7] op_sel_hi:[1,0,1] neg_lo:[0,0,1] neg_hi:[0,0,1]
	s_nop 0
	v_pk_mul_f32 v[6:7], v[12:13], v[12:13]
	s_nop 0
	v_add_f32_e32 v6, v8, v6
	v_add_f32_e32 v8, v6, v7
	ds_read2_b32 v[6:7], v9 offset0:64 offset1:96
	s_waitcnt lgkmcnt(0)
	v_pk_fma_f32 v[10:11], v[26:27], v[0:1], v[6:7] op_sel_hi:[1,0,1] neg_lo:[0,0,1] neg_hi:[0,0,1]
	s_nop 0
	v_pk_mul_f32 v[6:7], v[10:11], v[10:11]
	s_nop 0
	v_add_f32_e32 v6, v8, v6
	v_add_f32_e32 v16, v6, v7
	ds_read2_b32 v[6:7], v2 offset1:32
	s_waitcnt lgkmcnt(0)
	v_pk_fma_f32 v[8:9], v[28:29], v[0:1], v[6:7] op_sel_hi:[1,0,1] neg_lo:[0,0,1] neg_hi:[0,0,1]
	s_nop 0
	v_pk_mul_f32 v[6:7], v[8:9], v[8:9]
	s_nop 0
	v_add_f32_e32 v6, v16, v6
	v_add_f32_e32 v18, v6, v7
	ds_read2_b32 v[6:7], v2 offset0:64 offset1:96
	s_waitcnt lgkmcnt(0)
	v_pk_fma_f32 v[6:7], v[30:31], v[0:1], v[6:7] op_sel_hi:[1,0,1] neg_lo:[0,0,1] neg_hi:[0,0,1]
	s_nop 0
	v_pk_mul_f32 v[16:17], v[6:7], v[6:7]
	s_nop 0
	v_add_f32_e32 v0, v18, v16
	v_add_f32_e32 v0, v0, v17
	ds_bpermute_b32 v2, v5, v0
	s_waitcnt lgkmcnt(0)
	v_add_f32_e32 v0, v0, v2
	v_fmamk_f32 v0, v0, 0x3c000000, v174
	v_cmp_gt_f32_e32 vcc, s90, v0
	v_mul_f32_e32 v2, 0x4b800000, v0
	s_nop 0
	v_cndmask_b32_e32 v0, v0, v2, vcc
	v_rsq_f32_e32 v0, v0
	s_nop 0
	v_mul_f32_e32 v2, 0x45800000, v0
	v_cndmask_b32_e32 v0, v0, v2, vcc
	v_mul_f32_e32 v18, v3, v0
	v_lshl_or_b32 v0, s5, 5, v4
	v_or_b32_e32 v0, s22, v0
	v_lshlrev_b64 v[2:3], 11, v[0:1]
	v_lshl_add_u64 v[2:3], s[84:85], 0, v[2:3]
	s_mov_b32 s5, s81
	v_lshl_add_u64 v[16:17], v[2:3], 0, s[4:5]
	global_load_dwordx4 v[2:5], v21, s[2:3]
	global_load_dwordx4 v[196:199], v21, s[2:3] offset:32
	global_load_dwordx4 v[200:203], v21, s[2:3] offset:64
	global_load_dwordx4 v[204:207], v21, s[2:3] offset:96
	global_load_dwordx4 v[208:211], v21, s[2:3] offset:128
	global_load_dwordx4 v[212:215], v21, s[2:3] offset:160
	global_load_dwordx4 v[216:219], v21, s[2:3] offset:192
	global_load_dwordx4 v[220:223], v21, s[2:3] offset:224
	global_load_dwordx4 v[224:227], v21, s[2:3] offset:256
	global_load_dwordx4 v[228:231], v21, s[2:3] offset:288
	global_load_dwordx4 v[232:235], v21, s[2:3] offset:320
	global_load_dwordx4 v[236:239], v21, s[2:3] offset:352
	global_load_dwordx4 v[244:247], v21, s[2:3] offset:384
	global_load_dwordx4 v[248:251], v21, s[2:3] offset:416
	global_load_dwordx4 v[252:255], v21, s[2:3] offset:448
	global_load_dwordx4 v[148:151], v21, s[2:3] offset:480
	v_mul_f32_e32 v0, v81, v18
	s_waitcnt vmcnt(0)
	v_mul_f32_e32 v0, v2, v0
	v_mul_f32_e32 v2, v64, v18
	v_mul_f32_e32 v2, v3, v2
	v_cvt_pk_bf16_f32 v22, v0, v2
	v_mul_f32_e32 v0, v65, v18
	v_mul_f32_e32 v0, v4, v0
	v_mul_f32_e32 v2, v66, v18
	v_mul_f32_e32 v2, v5, v2
	v_cvt_pk_bf16_f32 v23, v0, v2
	v_lshlrev_b32_e32 v0, 3, v80
	v_lshl_add_u64 v[2:3], v[16:17], 0, v[0:1]
	global_store_dwordx2 v[2:3], v[22:23], off
	s_nop 0
	v_mul_f32_e32 v0, v67, v18
	v_mul_f32_e32 v4, v68, v18
	v_mul_f32_e32 v5, v70, v18
	s_nop 1
	v_mov_b32_e32 v22, v196
	v_mov_b32_e32 v23, v197
	v_mov_b32_e32 v24, v198
	v_mov_b32_e32 v25, v199
	s_nop 0
	v_mul_f32_e32 v0, v22, v0
	v_mul_f32_e32 v4, v23, v4
	v_cvt_pk_bf16_f32 v4, v0, v4
	v_mul_f32_e32 v0, v69, v18
	v_mul_f32_e32 v5, v25, v5
	v_mul_f32_e32 v0, v24, v0
	v_cvt_pk_bf16_f32 v5, v0, v5
	global_store_dwordx2 v[2:3], v[4:5], off offset:16
	s_nop 0
	v_mul_f32_e32 v0, v72, v18
	v_mul_f32_e32 v4, v71, v18
	v_mul_f32_e32 v5, v75, v18
	s_nop 1
	v_mov_b32_e32 v22, v200
	v_mov_b32_e32 v23, v201
	v_mov_b32_e32 v24, v202
	v_mov_b32_e32 v25, v203
	s_nop 0
	v_mul_f32_e32 v0, v22, v0
	v_mul_f32_e32 v4, v23, v4
	v_cvt_pk_bf16_f32 v4, v0, v4
	v_mul_f32_e32 v0, v82, v18
	v_mul_f32_e32 v5, v25, v5
	v_mul_f32_e32 v0, v24, v0
	v_cvt_pk_bf16_f32 v5, v0, v5
	global_store_dwordx2 v[2:3], v[4:5], off offset:32
	s_nop 0
	v_mul_f32_e32 v0, v74, v18
	v_mul_f32_e32 v4, v73, v18
	v_mul_f32_e32 v5, v77, v18
	s_nop 1
	v_mov_b32_e32 v22, v204
	v_mov_b32_e32 v23, v205
	v_mov_b32_e32 v24, v206
	v_mov_b32_e32 v25, v207
	s_nop 0
	v_mul_f32_e32 v0, v0, v22
	v_mul_f32_e32 v4, v4, v23
	v_cvt_pk_bf16_f32 v4, v0, v4
	v_mul_f32_e32 v0, v78, v18
	v_mul_f32_e32 v5, v5, v25
	v_mul_f32_e32 v0, v0, v24
	v_cvt_pk_bf16_f32 v5, v0, v5
	global_store_dwordx2 v[2:3], v[4:5], off offset:48
	s_nop 0
	v_mul_f32_e32 v0, v76, v18
	v_mul_f32_e32 v4, v48, v18
	v_mul_f32_e32 v5, v51, v18
	s_nop 1
	v_mov_b32_e32 v22, v208
	v_mov_b32_e32 v23, v209
	v_mov_b32_e32 v24, v210
	v_mov_b32_e32 v25, v211
	s_nop 0
	v_mul_f32_e32 v0, v0, v22
	v_mul_f32_e32 v4, v4, v23
	v_cvt_pk_bf16_f32 v4, v0, v4
	v_mul_f32_e32 v0, v79, v18
	v_mul_f32_e32 v5, v5, v25
	v_mul_f32_e32 v0, v0, v24
	v_cvt_pk_bf16_f32 v5, v0, v5
	global_store_dwordx2 v[2:3], v[4:5], off offset:64
	s_nop 0
	v_mul_f32_e32 v0, v50, v18
	v_mul_f32_e32 v4, v49, v18
	v_mul_f32_e32 v5, v54, v18
	s_nop 1
	v_mov_b32_e32 v22, v212
	v_mov_b32_e32 v23, v213
	v_mov_b32_e32 v24, v214
	v_mov_b32_e32 v25, v215
	s_nop 0
	v_mul_f32_e32 v0, v0, v22
	v_mul_f32_e32 v4, v4, v23
	v_cvt_pk_bf16_f32 v4, v0, v4
	v_mul_f32_e32 v0, v83, v18
	v_mul_f32_e32 v5, v5, v25
	v_mul_f32_e32 v0, v0, v24
	v_cvt_pk_bf16_f32 v5, v0, v5
	global_store_dwordx2 v[2:3], v[4:5], off offset:80
	s_nop 0
	v_mul_f32_e32 v0, v53, v18
	v_mul_f32_e32 v4, v52, v18
	v_mul_f32_e32 v5, v57, v18
	s_nop 1
	v_mov_b32_e32 v22, v216
	v_mov_b32_e32 v23, v217
	v_mov_b32_e32 v24, v218
	v_mov_b32_e32 v25, v219
	s_nop 0
	v_mul_f32_e32 v0, v0, v22
	v_mul_f32_e32 v4, v4, v23
	v_cvt_pk_bf16_f32 v4, v0, v4
	v_mul_f32_e32 v0, v58, v18
	v_mul_f32_e32 v5, v5, v25
	v_mul_f32_e32 v0, v0, v24
	v_cvt_pk_bf16_f32 v5, v0, v5
	global_store_dwordx2 v[2:3], v[4:5], off offset:96
	s_nop 0
	v_mul_f32_e32 v0, v56, v18
	v_mul_f32_e32 v4, v55, v18
	v_mul_f32_e32 v5, v60, v18
	s_nop 1
	v_mov_b32_e32 v22, v220
	v_mov_b32_e32 v23, v221
	v_mov_b32_e32 v24, v222
	v_mov_b32_e32 v25, v223
	s_nop 0
	v_mul_f32_e32 v0, v0, v22
	v_mul_f32_e32 v4, v4, v23
	v_cvt_pk_bf16_f32 v4, v0, v4
	v_mul_f32_e32 v0, v61, v18
	v_mul_f32_e32 v5, v5, v25
	v_mul_f32_e32 v0, v0, v24
	v_cvt_pk_bf16_f32 v5, v0, v5
	global_store_dwordx2 v[2:3], v[4:5], off offset:112
	s_nop 0
	v_mul_f32_e32 v0, v59, v18
	v_mul_f32_e32 v4, v32, v18
	v_mul_f32_e32 v5, v62, v18
	s_nop 1
	v_mov_b32_e32 v22, v224
	v_mov_b32_e32 v23, v225
	v_mov_b32_e32 v24, v226
	v_mov_b32_e32 v25, v227
	s_nop 0
	v_mul_f32_e32 v0, v0, v22
	v_mul_f32_e32 v4, v4, v23
	v_cvt_pk_bf16_f32 v4, v0, v4
	v_mul_f32_e32 v0, v63, v18
	v_mul_f32_e32 v5, v5, v25
	v_mul_f32_e32 v0, v0, v24
	v_cvt_pk_bf16_f32 v5, v0, v5
	global_store_dwordx2 v[2:3], v[4:5], off offset:128
	s_nop 0
	v_mul_f32_e32 v0, v36, v18
	v_mul_f32_e32 v4, v34, v18
	v_mul_f32_e32 v5, v84, v18
	s_nop 1
	v_mov_b32_e32 v22, v228
	v_mov_b32_e32 v23, v229
	v_mov_b32_e32 v24, v230
	v_mov_b32_e32 v25, v231
	s_nop 0
	v_mul_f32_e32 v0, v0, v22
	v_mul_f32_e32 v4, v4, v23
	v_cvt_pk_bf16_f32 v4, v0, v4
	v_mul_f32_e32 v0, v85, v18
	v_mul_f32_e32 v5, v5, v25
	v_mul_f32_e32 v0, v0, v24
	v_cvt_pk_bf16_f32 v5, v0, v5
	global_store_dwordx2 v[2:3], v[4:5], off offset:144
	s_nop 0
	v_mul_f32_e32 v0, v40, v18
	v_mul_f32_e32 v4, v39, v18
	v_mul_f32_e32 v5, v86, v18
	s_nop 1
	v_mov_b32_e32 v22, v232
	v_mov_b32_e32 v23, v233
	v_mov_b32_e32 v24, v234
	v_mov_b32_e32 v25, v235
	s_nop 0
	v_mul_f32_e32 v0, v0, v22
	v_mul_f32_e32 v4, v4, v23
	v_cvt_pk_bf16_f32 v4, v0, v4
	v_mul_f32_e32 v0, v87, v18
	v_mul_f32_e32 v5, v5, v25
	v_mul_f32_e32 v0, v0, v24
	v_cvt_pk_bf16_f32 v5, v0, v5
	global_store_dwordx2 v[2:3], v[4:5], off offset:160
	s_nop 0
	v_mul_f32_e32 v0, v44, v18
	v_mul_f32_e32 v4, v43, v18
	v_mul_f32_e32 v5, v41, v18
	s_nop 1
	v_mov_b32_e32 v22, v236
	v_mov_b32_e32 v23, v237
	v_mov_b32_e32 v24, v238
	v_mov_b32_e32 v25, v239
	s_nop 0
	v_mul_f32_e32 v0, v0, v22
	v_mul_f32_e32 v4, v4, v23
	v_cvt_pk_bf16_f32 v4, v0, v4
	v_mul_f32_e32 v0, v42, v18
	v_mul_f32_e32 v5, v5, v25
	v_mul_f32_e32 v0, v0, v24
	v_cvt_pk_bf16_f32 v5, v0, v5
	global_store_dwordx2 v[2:3], v[4:5], off offset:176
	s_nop 0
	v_mul_f32_e32 v0, v38, v18
	v_mul_f32_e32 v4, v37, v18
	v_mul_f32_e32 v5, v33, v18
	s_nop 1
	v_mov_b32_e32 v22, v244
	v_mov_b32_e32 v23, v245
	v_mov_b32_e32 v24, v246
	v_mov_b32_e32 v25, v247
	s_nop 0
	v_mul_f32_e32 v0, v0, v22
	v_mul_f32_e32 v4, v4, v23
	v_cvt_pk_bf16_f32 v4, v0, v4
	v_mul_f32_e32 v0, v35, v18
	v_mul_f32_e32 v5, v5, v25
	v_mul_f32_e32 v0, v0, v24
	v_cvt_pk_bf16_f32 v5, v0, v5
	global_store_dwordx2 v[2:3], v[4:5], off offset:192
	s_nop 0
	v_mul_f32_e32 v0, v20, v18
	v_mul_f32_e32 v4, v19, v18
	v_mul_f32_e32 v5, v15, v18
	s_nop 1
	v_mov_b32_e32 v22, v248
	v_mov_b32_e32 v23, v249
	v_mov_b32_e32 v24, v250
	v_mov_b32_e32 v25, v251
	s_nop 0
	v_mul_f32_e32 v0, v0, v22
	v_mul_f32_e32 v4, v4, v23
	v_cvt_pk_bf16_f32 v4, v0, v4
	v_mul_f32_e32 v0, v14, v18
	v_mul_f32_e32 v5, v5, v25
	v_mul_f32_e32 v0, v0, v24
	v_cvt_pk_bf16_f32 v5, v0, v5
	global_store_dwordx2 v[2:3], v[4:5], off offset:208
	s_nop 0
	v_mul_f32_e32 v0, v12, v18
	v_mul_f32_e32 v4, v13, v18
	v_mul_f32_e32 v5, v11, v18
	s_nop 1
	v_mov_b32_e32 v14, v252
	v_mov_b32_e32 v15, v253
	v_mov_b32_e32 v16, v254
	v_mov_b32_e32 v17, v255
	s_nop 0
	v_mul_f32_e32 v0, v0, v14
	v_mul_f32_e32 v4, v4, v15
	v_cvt_pk_bf16_f32 v4, v0, v4
	v_mul_f32_e32 v0, v10, v18
	v_mul_f32_e32 v5, v5, v17
	v_mul_f32_e32 v0, v0, v16
	v_cvt_pk_bf16_f32 v5, v0, v5
	global_store_dwordx2 v[2:3], v[4:5], off offset:224
	s_nop 0
	v_mul_f32_e32 v0, v8, v18
	v_mul_f32_e32 v4, v9, v18
	v_mul_f32_e32 v5, v7, v18
	s_nop 1
	v_mov_b32_e32 v10, v148
	v_mov_b32_e32 v11, v149
	v_mov_b32_e32 v12, v150
	v_mov_b32_e32 v13, v151
	s_nop 0
	v_mul_f32_e32 v0, v0, v10
	v_mul_f32_e32 v4, v4, v11
	v_cvt_pk_bf16_f32 v4, v0, v4
	v_mul_f32_e32 v0, v6, v18
	v_mul_f32_e32 v5, v5, v13
	v_mul_f32_e32 v0, v0, v12
	v_cvt_pk_bf16_f32 v5, v0, v5
	global_store_dwordx2 v[2:3], v[4:5], off offset:240
	s_branch .LBB0_198

	.amdhsa_kernel _Z8yoco_fwd6Params
		.amdhsa_group_segment_fixed_size 0
		.amdhsa_private_segment_fixed_size 0
		.amdhsa_kernarg_size 488
		.amdhsa_user_sgpr_count 2
		.amdhsa_user_sgpr_dispatch_ptr 0
		.amdhsa_user_sgpr_queue_ptr 0
		.amdhsa_user_sgpr_kernarg_segment_ptr 1
		.amdhsa_user_sgpr_dispatch_id 0
		.amdhsa_user_sgpr_kernarg_preload_length 0
		.amdhsa_user_sgpr_kernarg_preload_offset 0
		.amdhsa_user_sgpr_private_segment_size 0
		.amdhsa_uses_dynamic_stack 0
		.amdhsa_enable_private_segment 0
		.amdhsa_system_sgpr_workgroup_id_x 1
		.amdhsa_system_sgpr_workgroup_id_y 0
		.amdhsa_system_sgpr_workgroup_id_z 0
		.amdhsa_system_sgpr_workgroup_info 0
		.amdhsa_system_vgpr_workitem_id 2
		.amdhsa_next_free_vgpr 256
		.amdhsa_next_free_sgpr 102
		.amdhsa_accum_offset 256
		.amdhsa_reserve_vcc 1
		.amdhsa_float_round_mode_32 0
		.amdhsa_float_round_mode_16_64 0
		.amdhsa_float_denorm_mode_32 3
		.amdhsa_float_denorm_mode_16_64 3
		.amdhsa_dx10_clamp 1
		.amdhsa_ieee_mode 1
		.amdhsa_fp16_overflow 0
		.amdhsa_tg_split 0
		.amdhsa_exception_fp_ieee_invalid_op 0
		.amdhsa_exception_fp_denorm_src 0
		.amdhsa_exception_fp_ieee_div_zero 0
		.amdhsa_exception_fp_ieee_overflow 0
		.amdhsa_exception_fp_ieee_underflow 0
		.amdhsa_exception_fp_ieee_inexact 0
		.amdhsa_exception_int_div_zero 0
	.end_amdhsa_kernel

amdhsa.kernels:
  - .agpr_count:     0
    .args:
      - .offset:         0
        .size:           232
        .value_kind:     by_value
      - .offset:         232
        .size:           4
        .value_kind:     hidden_block_count_x
      - .offset:         236
        .size:           4
        .value_kind:     hidden_block_count_y
      - .offset:         240
        .size:           4
        .value_kind:     hidden_block_count_z
      - .offset:         244
        .size:           2
        .value_kind:     hidden_group_size_x
      - .offset:         246
        .size:           2
        .value_kind:     hidden_group_size_y
      - .offset:         248
        .size:           2
        .value_kind:     hidden_group_size_z
      - .offset:         250
        .size:           2
        .value_kind:     hidden_remainder_x
      - .offset:         252
        .size:           2
        .value_kind:     hidden_remainder_y
      - .offset:         254
        .size:           2
        .value_kind:     hidden_remainder_z
      - .offset:         272
        .size:           8
        .value_kind:     hidden_global_offset_x
      - .offset:         280
        .size:           8
        .value_kind:     hidden_global_offset_y
      - .offset:         288
        .size:           8
        .value_kind:     hidden_global_offset_z
      - .offset:         296
        .size:           2
        .value_kind:     hidden_grid_dims
      - .offset:         320
        .size:           8
        .value_kind:     hidden_multigrid_sync_arg
      - .offset:         352
        .size:           4
        .value_kind:     hidden_dynamic_lds_size
    .group_segment_fixed_size: 0
    .kernarg_segment_align: 8
    .kernarg_segment_size: 488
    .language:       OpenCL C
    .language_version:
      - 2
      - 0
    .max_flat_workgroup_size: 512
    .name:           _Z8yoco_fwd6Params
    .private_segment_fixed_size: 0
    .sgpr_count:     108
    .sgpr_spill_count: 250
    .symbol:         _Z8yoco_fwd6Params.kd
    .uniform_work_group_size: 1
    .uses_dynamic_stack: false
    .vgpr_count:     256
    .vgpr_spill_count: 0
    .wavefront_size: 64
